# nt hint on the once-read f32 weight loads of the conversion loops (init and deferred conversion jobs)
# speedup vs baseline: 1.0286x; 1.0157x over previous
.LBB0_34:
	s_or_b64 exec, exec, s[4:5]
	v_cmp_lt_i32_e64 s[4:5], -1, v32
	v_lshlrev_b32_e32 v34, 3, v41
	v_lshl_add_u64 v[36:37], v[32:33], 2, s[82:83]
	v_mov_b32_e32 v4, 0
	v_mov_b32_e32 v0, 0
	v_mov_b32_e32 v1, 0
	v_mov_b32_e32 v2, 0
	v_mov_b32_e32 v3, 0
	s_and_saveexec_b64 s[10:11], s[4:5]
	s_cbranch_execz .LBB0_37
	v_mad_i64_i32 v[0:1], s[12:13], v34, s24, v[36:37]
	global_load_dwordx4 v[0:3], v[0:1], off nt
	s_and_b64 vcc, exec, s[74:75]
	s_cbranch_vccnz .LBB0_37
	v_ashrrev_i32_e32 v35, 31, v34
	v_lshl_add_u64 v[6:7], v[34:35], 2, s[86:87]
	global_load_dword v50, v[6:7], off
.LBB0_37:
	s_or_b64 exec, exec, s[10:11]
	v_mov_b32_e32 v5, 0
	v_mov_b32_e32 v6, 0
	v_mov_b32_e32 v7, 0
	s_and_saveexec_b64 s[10:11], s[4:5]
	s_cbranch_execz .LBB0_40
	v_or_b32_e32 v4, 1, v34
	v_mad_i64_i32 v[4:5], s[12:13], v4, s24, v[36:37]
	global_load_dwordx4 v[4:7], v[4:5], off nt
	s_and_b64 vcc, exec, s[74:75]
	s_cbranch_vccnz .LBB0_40
	v_ashrrev_i32_e32 v35, 31, v34
	v_lshl_add_u64 v[8:9], v[34:35], 2, s[86:87]
	global_load_dword v51, v[8:9], off offset:4
.LBB0_40:
	s_or_b64 exec, exec, s[10:11]
	v_mov_b32_e32 v8, 0
	v_mov_b32_e32 v12, 0
	v_mov_b32_e32 v13, 0
	v_mov_b32_e32 v14, 0
	v_mov_b32_e32 v15, 0
	s_and_saveexec_b64 s[10:11], s[4:5]
	s_cbranch_execz .LBB0_43
	v_or_b32_e32 v9, 2, v34
	v_mad_i64_i32 v[10:11], s[12:13], v9, s24, v[36:37]
	global_load_dwordx4 v[12:15], v[10:11], off nt
	s_and_b64 vcc, exec, s[74:75]
	s_cbranch_vccnz .LBB0_43
	v_ashrrev_i32_e32 v35, 31, v34
	v_lshl_add_u64 v[10:11], v[34:35], 2, s[86:87]
	global_load_dword v52, v[10:11], off offset:8
.LBB0_43:
	s_or_b64 exec, exec, s[10:11]
	v_mov_b32_e32 v9, 0
	v_mov_b32_e32 v10, 0
	v_mov_b32_e32 v11, 0
	s_and_saveexec_b64 s[10:11], s[4:5]
	s_cbranch_execz .LBB0_46
	v_or_b32_e32 v8, 3, v34
	v_mad_i64_i32 v[8:9], s[12:13], v8, s24, v[36:37]
	global_load_dwordx4 v[8:11], v[8:9], off nt
	s_and_b64 vcc, exec, s[74:75]
	s_cbranch_vccnz .LBB0_46
	v_ashrrev_i32_e32 v35, 31, v34
	v_lshl_add_u64 v[16:17], v[34:35], 2, s[86:87]
	global_load_dword v53, v[16:17], off offset:12
.LBB0_46:
	s_or_b64 exec, exec, s[10:11]
	v_mov_b32_e32 v16, 0
	v_mov_b32_e32 v20, 0
	v_mov_b32_e32 v21, 0
	v_mov_b32_e32 v22, 0
	v_mov_b32_e32 v23, 0
	s_and_saveexec_b64 s[10:11], s[4:5]
	s_cbranch_execz .LBB0_49
	v_or_b32_e32 v17, 4, v34
	v_mad_i64_i32 v[18:19], s[12:13], v17, s24, v[36:37]
	global_load_dwordx4 v[20:23], v[18:19], off nt
	s_and_b64 vcc, exec, s[74:75]
	s_cbranch_vccnz .LBB0_49
	v_ashrrev_i32_e32 v35, 31, v34
	v_lshl_add_u64 v[18:19], v[34:35], 2, s[86:87]
	global_load_dword v54, v[18:19], off offset:16
.LBB0_49:
	s_or_b64 exec, exec, s[10:11]
	v_mov_b32_e32 v17, 0
	v_mov_b32_e32 v18, 0
	v_mov_b32_e32 v19, 0
	s_and_saveexec_b64 s[10:11], s[4:5]
	s_cbranch_execz .LBB0_52
	v_or_b32_e32 v16, 5, v34
	v_mad_i64_i32 v[16:17], s[12:13], v16, s24, v[36:37]
	global_load_dwordx4 v[16:19], v[16:17], off nt
	s_and_b64 vcc, exec, s[74:75]
	s_cbranch_vccnz .LBB0_52
	v_ashrrev_i32_e32 v35, 31, v34
	v_lshl_add_u64 v[24:25], v[34:35], 2, s[86:87]
	global_load_dword v55, v[24:25], off offset:20
.LBB0_52:
	s_or_b64 exec, exec, s[10:11]
	v_mov_b32_e32 v24, 0
	v_mov_b32_e32 v28, 0
	v_mov_b32_e32 v29, 0
	v_mov_b32_e32 v30, 0
	v_mov_b32_e32 v31, 0
	s_and_saveexec_b64 s[10:11], s[4:5]
	s_cbranch_execz .LBB0_55
	v_or_b32_e32 v25, 6, v34
	v_mad_i64_i32 v[26:27], s[12:13], v25, s24, v[36:37]
	global_load_dwordx4 v[28:31], v[26:27], off nt
	s_and_b64 vcc, exec, s[74:75]
	s_cbranch_vccnz .LBB0_55
	v_ashrrev_i32_e32 v35, 31, v34
	v_lshl_add_u64 v[26:27], v[34:35], 2, s[86:87]
	global_load_dword v56, v[26:27], off offset:24
.LBB0_55:
	s_or_b64 exec, exec, s[10:11]
	v_mov_b32_e32 v25, 0
	v_mov_b32_e32 v26, 0
	v_mov_b32_e32 v27, 0
	s_and_saveexec_b64 s[10:11], s[4:5]
	s_cbranch_execz .LBB0_19
	v_or_b32_e32 v24, 7, v34
	v_mad_i64_i32 v[24:25], s[4:5], v24, s24, v[36:37]
	global_load_dwordx4 v[24:27], v[24:25], off nt
	s_and_b64 vcc, exec, s[74:75]
	s_cbranch_vccnz .LBB0_19
	v_ashrrev_i32_e32 v35, 31, v34
	v_lshl_add_u64 v[34:35], v[34:35], 2, s[86:87]
	global_load_dword v57, v[34:35], off offset:28
	s_waitcnt vmcnt(0)
	v_mul_f32_e32 v2, v2, v50
	v_mul_f32_e32 v3, v3, v50
	v_mul_f32_e32 v0, v0, v50
	v_mul_f32_e32 v1, v1, v50
	v_mul_f32_e32 v6, v6, v51
	v_mul_f32_e32 v7, v7, v51
	v_mul_f32_e32 v4, v4, v51
	v_mul_f32_e32 v5, v5, v51
	v_mul_f32_e32 v14, v14, v52
	v_mul_f32_e32 v15, v15, v52
	v_mul_f32_e32 v12, v12, v52
	v_mul_f32_e32 v13, v13, v52
	v_mul_f32_e32 v10, v10, v53
	v_mul_f32_e32 v11, v11, v53
	v_mul_f32_e32 v8, v8, v53
	v_mul_f32_e32 v9, v9, v53
	v_mul_f32_e32 v22, v22, v54
	v_mul_f32_e32 v23, v23, v54
	v_mul_f32_e32 v20, v20, v54
	v_mul_f32_e32 v21, v21, v54
	v_mul_f32_e32 v18, v18, v55
	v_mul_f32_e32 v19, v19, v55
	v_mul_f32_e32 v16, v16, v55
	v_mul_f32_e32 v17, v17, v55
	v_mul_f32_e32 v30, v30, v56
	v_mul_f32_e32 v31, v31, v56
	v_mul_f32_e32 v28, v28, v56
	v_mul_f32_e32 v29, v29, v56
	v_mul_f32_e32 v26, v26, v57
	v_mul_f32_e32 v27, v27, v57
	v_mul_f32_e32 v24, v24, v57
	v_mul_f32_e32 v25, v25, v57
	s_branch .LBB0_19

.LBB0_61:
	v_mul_hi_i32 v0, v34, s15
	v_lshrrev_b32_e32 v1, 31, v0
	v_ashrrev_i32_e32 v0, 4, v0
	v_add_u32_e32 v2, v0, v1
	v_mad_u64_u32 v[36:37], s[0:1], v2, s17, v[32:33]
	v_mad_u64_u32 v[0:1], s[0:1], v2, s16, v[34:35]
	v_lshlrev_b32_e32 v38, 3, v2
	v_mov_b32_e32 v37, v33
	v_cmp_lt_i32_e64 s[0:1], -1, v0
	v_lshl_add_u64 v[40:41], v[36:37], 2, s[94:95]
	v_ashrrev_i32_e32 v39, 31, v38
	v_mov_b32_e32 v0, 0
	v_mov_b32_e32 v1, 0
	v_mov_b32_e32 v2, 0
	v_mov_b32_e32 v3, 0
	s_and_saveexec_b64 s[12:13], s[0:1]
	s_cbranch_execz .LBB0_64
	v_mad_i64_i32 v[0:1], s[20:21], v38, s18, v[40:41]
	global_load_dwordx4 v[0:3], v[0:1], off nt
	s_and_b64 vcc, exec, s[4:5]
	s_cbranch_vccnz .LBB0_64
	v_lshl_add_u64 v[4:5], v[38:39], 2, s[90:91]
	global_load_dword v50, v[4:5], off
.LBB0_64:
	s_or_b64 exec, exec, s[12:13]
	v_mov_b32_e32 v4, 0
	v_mov_b32_e32 v8, 0
	v_mov_b32_e32 v9, 0
	v_mov_b32_e32 v10, 0
	v_mov_b32_e32 v11, 0
	s_and_saveexec_b64 s[12:13], s[0:1]
	s_cbranch_execz .LBB0_67
	v_or_b32_e32 v5, 1, v38
	v_mad_i64_i32 v[6:7], s[20:21], v5, s18, v[40:41]
	global_load_dwordx4 v[8:11], v[6:7], off nt
	s_and_b64 vcc, exec, s[4:5]
	s_cbranch_vccnz .LBB0_67
	v_lshl_add_u64 v[6:7], v[38:39], 2, s[90:91]
	global_load_dword v51, v[6:7], off offset:4
.LBB0_67:
	s_or_b64 exec, exec, s[12:13]
	v_mov_b32_e32 v5, 0
	v_mov_b32_e32 v6, 0
	v_mov_b32_e32 v7, 0
	s_and_saveexec_b64 s[12:13], s[0:1]
	s_cbranch_execz .LBB0_70
	v_or_b32_e32 v4, 2, v38
	v_mad_i64_i32 v[4:5], s[20:21], v4, s18, v[40:41]
	global_load_dwordx4 v[4:7], v[4:5], off nt
	s_and_b64 vcc, exec, s[4:5]
	s_cbranch_vccnz .LBB0_70
	v_lshl_add_u64 v[12:13], v[38:39], 2, s[90:91]
	global_load_dword v52, v[12:13], off offset:8
.LBB0_70:
	s_or_b64 exec, exec, s[12:13]
	v_mov_b32_e32 v12, 0
	v_mov_b32_e32 v16, 0
	v_mov_b32_e32 v17, 0
	v_mov_b32_e32 v18, 0
	v_mov_b32_e32 v19, 0
	s_and_saveexec_b64 s[12:13], s[0:1]
	s_cbranch_execz .LBB0_73
	v_or_b32_e32 v13, 3, v38
	v_mad_i64_i32 v[14:15], s[20:21], v13, s18, v[40:41]
	global_load_dwordx4 v[16:19], v[14:15], off nt
	s_and_b64 vcc, exec, s[4:5]
	s_cbranch_vccnz .LBB0_73
	v_lshl_add_u64 v[14:15], v[38:39], 2, s[90:91]
	global_load_dword v53, v[14:15], off offset:12
.LBB0_73:
	s_or_b64 exec, exec, s[12:13]
	v_mov_b32_e32 v13, 0
	v_mov_b32_e32 v14, 0
	v_mov_b32_e32 v15, 0
	s_and_saveexec_b64 s[12:13], s[0:1]
	s_cbranch_execz .LBB0_76
	v_or_b32_e32 v12, 4, v38
	v_mad_i64_i32 v[12:13], s[20:21], v12, s18, v[40:41]
	global_load_dwordx4 v[12:15], v[12:13], off nt
	s_and_b64 vcc, exec, s[4:5]
	s_cbranch_vccnz .LBB0_76
	v_lshl_add_u64 v[20:21], v[38:39], 2, s[90:91]
	global_load_dword v54, v[20:21], off offset:16
.LBB0_76:
	s_or_b64 exec, exec, s[12:13]
	v_mov_b32_e32 v20, 0
	v_mov_b32_e32 v24, 0
	v_mov_b32_e32 v25, 0
	v_mov_b32_e32 v26, 0
	v_mov_b32_e32 v27, 0
	s_and_saveexec_b64 s[12:13], s[0:1]
	s_cbranch_execz .LBB0_79
	v_or_b32_e32 v21, 5, v38
	v_mad_i64_i32 v[22:23], s[20:21], v21, s18, v[40:41]
	global_load_dwordx4 v[24:27], v[22:23], off nt
	s_and_b64 vcc, exec, s[4:5]
	s_cbranch_vccnz .LBB0_79
	v_lshl_add_u64 v[22:23], v[38:39], 2, s[90:91]
	global_load_dword v55, v[22:23], off offset:20
.LBB0_79:
	s_or_b64 exec, exec, s[12:13]
	v_mov_b32_e32 v21, 0
	v_mov_b32_e32 v22, 0
	v_mov_b32_e32 v23, 0
	s_and_saveexec_b64 s[12:13], s[0:1]
	s_cbranch_execz .LBB0_82
	v_or_b32_e32 v20, 6, v38
	v_mad_i64_i32 v[20:21], s[20:21], v20, s18, v[40:41]
	global_load_dwordx4 v[20:23], v[20:21], off nt
	s_and_b64 vcc, exec, s[4:5]
	s_cbranch_vccnz .LBB0_82
	v_lshl_add_u64 v[28:29], v[38:39], 2, s[90:91]
	global_load_dword v56, v[28:29], off offset:24
.LBB0_82:
	s_or_b64 exec, exec, s[12:13]
	v_mov_b32_e32 v28, 0
	v_mov_b32_e32 v29, 0
	v_mov_b32_e32 v30, 0
	v_mov_b32_e32 v31, 0
	s_and_saveexec_b64 s[12:13], s[0:1]
	s_cbranch_execz .LBB0_60
	v_or_b32_e32 v28, 7, v38
	v_mad_i64_i32 v[28:29], s[0:1], v28, s18, v[40:41]
	global_load_dwordx4 v[28:31], v[28:29], off nt
	s_and_b64 vcc, exec, s[4:5]
	s_cbranch_vccnz .LBB0_60
	v_lshl_add_u64 v[40:41], v[38:39], 2, s[90:91]
	global_load_dword v57, v[40:41], off offset:28
	s_waitcnt vmcnt(0)
	v_mul_f32_e32 v2, v2, v50
	v_mul_f32_e32 v3, v3, v50
	v_mul_f32_e32 v0, v0, v50
	v_mul_f32_e32 v1, v1, v50
	v_mul_f32_e32 v10, v10, v51
	v_mul_f32_e32 v11, v11, v51
	v_mul_f32_e32 v8, v8, v51
	v_mul_f32_e32 v9, v9, v51
	v_mul_f32_e32 v6, v6, v52
	v_mul_f32_e32 v7, v7, v52
	v_mul_f32_e32 v4, v4, v52
	v_mul_f32_e32 v5, v5, v52
	v_mul_f32_e32 v18, v18, v53
	v_mul_f32_e32 v19, v19, v53
	v_mul_f32_e32 v16, v16, v53
	v_mul_f32_e32 v17, v17, v53
	v_mul_f32_e32 v14, v14, v54
	v_mul_f32_e32 v15, v15, v54
	v_mul_f32_e32 v12, v12, v54
	v_mul_f32_e32 v13, v13, v54
	v_mul_f32_e32 v26, v26, v55
	v_mul_f32_e32 v27, v27, v55
	v_mul_f32_e32 v24, v24, v55
	v_mul_f32_e32 v25, v25, v55
	v_mul_f32_e32 v22, v22, v56
	v_mul_f32_e32 v23, v23, v56
	v_mul_f32_e32 v20, v20, v56
	v_mul_f32_e32 v21, v21, v56
	v_mul_f32_e32 v30, v30, v57
	v_mul_f32_e32 v31, v31, v57
	v_mul_f32_e32 v28, v28, v57
	v_mul_f32_e32 v29, v29, v57
	s_branch .LBB0_60

.LBB0_88:
	v_ashrrev_i32_e32 v0, 31, v39
	v_lshrrev_b32_e32 v0, 25, v0
	v_add_u32_e32 v0, v39, v0
	v_ashrrev_i32_e32 v1, 7, v0
	v_and_b32_e32 v0, 0xffffff80, v0
	v_lshlrev_b32_e32 v2, 9, v1
	v_readlane_b32 s40, v252, 10
	v_sub_u32_e32 v0, v39, v0
	v_sub_u32_e32 v32, v38, v2
	v_lshlrev_b32_e32 v34, 3, v1
	v_readlane_b32 s41, v252, 11
	v_cmp_lt_i32_e64 s[0:1], -1, v0
	v_ashrrev_i32_e32 v35, 31, v34
	v_lshl_add_u64 v[36:37], v[32:33], 2, s[40:41]
	v_mov_b32_e32 v0, 0
	v_mov_b32_e32 v1, 0
	v_mov_b32_e32 v2, 0
	v_mov_b32_e32 v3, 0
	v_readlane_b32 s42, v252, 12
	v_readlane_b32 s43, v252, 13
	v_readlane_b32 s44, v252, 14
	v_readlane_b32 s45, v252, 15
	v_readlane_b32 s46, v252, 16
	v_readlane_b32 s47, v252, 17
	v_readlane_b32 s48, v252, 18
	v_readlane_b32 s49, v252, 19
	v_readlane_b32 s50, v252, 20
	v_readlane_b32 s51, v252, 21
	v_readlane_b32 s52, v252, 22
	v_readlane_b32 s53, v252, 23
	v_readlane_b32 s54, v252, 24
	v_readlane_b32 s55, v252, 25
	s_and_saveexec_b64 s[14:15], s[0:1]
	s_cbranch_execz .LBB0_91
	v_lshlrev_b64 v[0:1], 11, v[34:35]
	v_lshl_add_u64 v[0:1], v[36:37], 0, v[0:1]
	global_load_dwordx4 v[0:3], v[0:1], off nt
	s_and_b64 vcc, exec, s[6:7]
	s_cbranch_vccnz .LBB0_91
	v_lshl_add_u64 v[4:5], v[34:35], 2, s[92:93]
	global_load_dword v50, v[4:5], off
.LBB0_91:
	s_or_b64 exec, exec, s[14:15]
	v_mov_b32_e32 v4, 0
	v_mov_b32_e32 v8, 0
	v_mov_b32_e32 v9, 0
	v_mov_b32_e32 v10, 0
	v_mov_b32_e32 v11, 0
	s_and_saveexec_b64 s[14:15], s[0:1]
	s_cbranch_execz .LBB0_94
	v_or_b32_e32 v6, 1, v34
	v_ashrrev_i32_e32 v7, 31, v6
	v_lshlrev_b64 v[6:7], 11, v[6:7]
	v_lshl_add_u64 v[6:7], v[36:37], 0, v[6:7]
	global_load_dwordx4 v[8:11], v[6:7], off nt
	s_and_b64 vcc, exec, s[6:7]
	s_cbranch_vccnz .LBB0_94
	v_lshl_add_u64 v[6:7], v[34:35], 2, s[92:93]
	global_load_dword v51, v[6:7], off offset:4
.LBB0_94:
	s_or_b64 exec, exec, s[14:15]
	v_mov_b32_e32 v5, 0
	v_mov_b32_e32 v6, 0
	v_mov_b32_e32 v7, 0
	s_and_saveexec_b64 s[14:15], s[0:1]
	s_cbranch_execz .LBB0_97
	v_or_b32_e32 v4, 2, v34
	v_ashrrev_i32_e32 v5, 31, v4
	v_lshlrev_b64 v[4:5], 11, v[4:5]
	v_lshl_add_u64 v[4:5], v[36:37], 0, v[4:5]
	global_load_dwordx4 v[4:7], v[4:5], off nt
	s_and_b64 vcc, exec, s[6:7]
	s_cbranch_vccnz .LBB0_97
	v_lshl_add_u64 v[12:13], v[34:35], 2, s[92:93]
	global_load_dword v52, v[12:13], off offset:8
.LBB0_97:
	s_or_b64 exec, exec, s[14:15]
	v_mov_b32_e32 v12, 0
	v_mov_b32_e32 v16, 0
	v_mov_b32_e32 v17, 0
	v_mov_b32_e32 v18, 0
	v_mov_b32_e32 v19, 0
	s_and_saveexec_b64 s[14:15], s[0:1]
	s_cbranch_execz .LBB0_100
	v_or_b32_e32 v14, 3, v34
	v_ashrrev_i32_e32 v15, 31, v14
	v_lshlrev_b64 v[14:15], 11, v[14:15]
	v_lshl_add_u64 v[14:15], v[36:37], 0, v[14:15]
	global_load_dwordx4 v[16:19], v[14:15], off nt
	s_and_b64 vcc, exec, s[6:7]
	s_cbranch_vccnz .LBB0_100
	v_lshl_add_u64 v[14:15], v[34:35], 2, s[92:93]
	global_load_dword v53, v[14:15], off offset:12
.LBB0_100:
	s_or_b64 exec, exec, s[14:15]
	v_mov_b32_e32 v13, 0
	v_mov_b32_e32 v14, 0
	v_mov_b32_e32 v15, 0
	s_and_saveexec_b64 s[14:15], s[0:1]
	s_cbranch_execz .LBB0_103
	v_or_b32_e32 v12, 4, v34
	v_ashrrev_i32_e32 v13, 31, v12
	v_lshlrev_b64 v[12:13], 11, v[12:13]
	v_lshl_add_u64 v[12:13], v[36:37], 0, v[12:13]
	global_load_dwordx4 v[12:15], v[12:13], off nt
	s_and_b64 vcc, exec, s[6:7]
	s_cbranch_vccnz .LBB0_103
	v_lshl_add_u64 v[20:21], v[34:35], 2, s[92:93]
	global_load_dword v54, v[20:21], off offset:16
.LBB0_103:
	s_or_b64 exec, exec, s[14:15]
	v_mov_b32_e32 v20, 0
	v_mov_b32_e32 v24, 0
	v_mov_b32_e32 v25, 0
	v_mov_b32_e32 v26, 0
	v_mov_b32_e32 v27, 0
	s_and_saveexec_b64 s[14:15], s[0:1]
	s_cbranch_execz .LBB0_106
	v_or_b32_e32 v22, 5, v34
	v_ashrrev_i32_e32 v23, 31, v22
	v_lshlrev_b64 v[22:23], 11, v[22:23]
	v_lshl_add_u64 v[22:23], v[36:37], 0, v[22:23]
	global_load_dwordx4 v[24:27], v[22:23], off nt
	s_and_b64 vcc, exec, s[6:7]
	s_cbranch_vccnz .LBB0_106
	v_lshl_add_u64 v[22:23], v[34:35], 2, s[92:93]
	global_load_dword v55, v[22:23], off offset:20
.LBB0_106:
	s_or_b64 exec, exec, s[14:15]
	v_mov_b32_e32 v21, 0
	v_mov_b32_e32 v22, 0
	v_mov_b32_e32 v23, 0
	s_and_saveexec_b64 s[14:15], s[0:1]
	s_cbranch_execz .LBB0_109
	v_or_b32_e32 v20, 6, v34
	v_ashrrev_i32_e32 v21, 31, v20
	v_lshlrev_b64 v[20:21], 11, v[20:21]
	v_lshl_add_u64 v[20:21], v[36:37], 0, v[20:21]
	global_load_dwordx4 v[20:23], v[20:21], off nt
	s_and_b64 vcc, exec, s[6:7]
	s_cbranch_vccnz .LBB0_109
	v_lshl_add_u64 v[28:29], v[34:35], 2, s[92:93]
	global_load_dword v56, v[28:29], off offset:24
.LBB0_109:
	s_or_b64 exec, exec, s[14:15]
	v_mov_b32_e32 v28, 0
	v_mov_b32_e32 v29, 0
	v_mov_b32_e32 v30, 0
	v_mov_b32_e32 v31, 0
	s_and_saveexec_b64 s[14:15], s[0:1]
	s_cbranch_execz .LBB0_87
	v_or_b32_e32 v28, 7, v34
	v_ashrrev_i32_e32 v29, 31, v28
	v_lshlrev_b64 v[28:29], 11, v[28:29]
	v_lshl_add_u64 v[28:29], v[36:37], 0, v[28:29]
	global_load_dwordx4 v[28:31], v[28:29], off nt
	s_and_b64 vcc, exec, s[6:7]
	s_cbranch_vccnz .LBB0_87
	v_lshl_add_u64 v[36:37], v[34:35], 2, s[92:93]
	global_load_dword v57, v[36:37], off offset:28
	s_waitcnt vmcnt(0)
	v_mul_f32_e32 v2, v2, v50
	v_mul_f32_e32 v3, v3, v50
	v_mul_f32_e32 v0, v0, v50
	v_mul_f32_e32 v1, v1, v50
	v_mul_f32_e32 v10, v10, v51
	v_mul_f32_e32 v11, v11, v51
	v_mul_f32_e32 v8, v8, v51
	v_mul_f32_e32 v9, v9, v51
	v_mul_f32_e32 v6, v6, v52
	v_mul_f32_e32 v7, v7, v52
	v_mul_f32_e32 v4, v4, v52
	v_mul_f32_e32 v5, v5, v52
	v_mul_f32_e32 v18, v18, v53
	v_mul_f32_e32 v19, v19, v53
	v_mul_f32_e32 v16, v16, v53
	v_mul_f32_e32 v17, v17, v53
	v_mul_f32_e32 v14, v14, v54
	v_mul_f32_e32 v15, v15, v54
	v_mul_f32_e32 v12, v12, v54
	v_mul_f32_e32 v13, v13, v54
	v_mul_f32_e32 v26, v26, v55
	v_mul_f32_e32 v27, v27, v55
	v_mul_f32_e32 v24, v24, v55
	v_mul_f32_e32 v25, v25, v55
	v_mul_f32_e32 v22, v22, v56
	v_mul_f32_e32 v23, v23, v56
	v_mul_f32_e32 v20, v20, v56
	v_mul_f32_e32 v21, v21, v56
	v_mul_f32_e32 v30, v30, v57
	v_mul_f32_e32 v31, v31, v57
	v_mul_f32_e32 v28, v28, v57
	v_mul_f32_e32 v29, v29, v57
	s_branch .LBB0_87

.LBB0_115:
	v_ashrrev_i32_e32 v0, 31, v45
	v_lshrrev_b32_e32 v0, 26, v0
	v_add_u32_e32 v0, v45, v0
	v_ashrrev_i32_e32 v46, 6, v0
	v_and_b32_e32 v0, 0xffffffc0, v0
	v_lshlrev_b32_e32 v1, 8, v46
	v_readlane_b32 s40, v252, 10
	v_sub_u32_e32 v0, v45, v0
	v_sub_u32_e32 v32, v41, v1
	v_readlane_b32 s46, v252, 16
	v_readlane_b32 s47, v252, 17
	v_cmp_lt_i32_e32 vcc, -1, v0
	v_lshlrev_b32_e32 v34, 3, v46
	v_lshl_add_u64 v[36:37], v[32:33], 2, s[46:47]
	v_mov_b32_e32 v0, 0
	v_mov_b32_e32 v1, 0
	v_mov_b32_e32 v2, 0
	v_mov_b32_e32 v3, 0
	v_readlane_b32 s41, v252, 11
	v_readlane_b32 s42, v252, 12
	v_readlane_b32 s43, v252, 13
	v_readlane_b32 s44, v252, 14
	v_readlane_b32 s45, v252, 15
	v_readlane_b32 s48, v252, 18
	v_readlane_b32 s49, v252, 19
	v_readlane_b32 s50, v252, 20
	v_readlane_b32 s51, v252, 21
	v_readlane_b32 s52, v252, 22
	v_readlane_b32 s53, v252, 23
	v_readlane_b32 s54, v252, 24
	v_readlane_b32 s55, v252, 25
	s_and_saveexec_b64 s[12:13], vcc
	s_cbranch_execz .LBB0_117
	v_ashrrev_i32_e32 v35, 31, v34
	v_lshlrev_b64 v[0:1], 10, v[34:35]
	v_lshl_add_u64 v[0:1], v[36:37], 0, v[0:1]
	global_load_dwordx4 v[0:3], v[0:1], off nt
.LBB0_117:
	s_or_b64 exec, exec, s[12:13]
	v_mov_b32_e32 v4, 0
	v_mov_b32_e32 v8, 0
	v_mov_b32_e32 v9, 0
	v_mov_b32_e32 v10, 0
	v_mov_b32_e32 v11, 0
	s_and_saveexec_b64 s[12:13], vcc
	s_cbranch_execz .LBB0_119
	v_or_b32_e32 v6, 1, v34
	v_ashrrev_i32_e32 v7, 31, v6
	v_lshlrev_b64 v[6:7], 10, v[6:7]
	v_lshl_add_u64 v[6:7], v[36:37], 0, v[6:7]
	global_load_dwordx4 v[8:11], v[6:7], off nt
.LBB0_119:
	s_or_b64 exec, exec, s[12:13]
	v_mov_b32_e32 v5, 0
	v_mov_b32_e32 v6, 0
	v_mov_b32_e32 v7, 0
	s_and_saveexec_b64 s[12:13], vcc
	s_cbranch_execz .LBB0_121
	v_or_b32_e32 v4, 2, v34
	v_ashrrev_i32_e32 v5, 31, v4
	v_lshlrev_b64 v[4:5], 10, v[4:5]
	v_lshl_add_u64 v[4:5], v[36:37], 0, v[4:5]
	global_load_dwordx4 v[4:7], v[4:5], off nt
.LBB0_121:
	s_or_b64 exec, exec, s[12:13]
	v_mov_b32_e32 v12, 0
	v_mov_b32_e32 v16, 0
	v_mov_b32_e32 v17, 0
	v_mov_b32_e32 v18, 0
	v_mov_b32_e32 v19, 0
	s_and_saveexec_b64 s[12:13], vcc
	s_cbranch_execz .LBB0_123
	v_or_b32_e32 v14, 3, v34
	v_ashrrev_i32_e32 v15, 31, v14
	v_lshlrev_b64 v[14:15], 10, v[14:15]
	v_lshl_add_u64 v[14:15], v[36:37], 0, v[14:15]
	global_load_dwordx4 v[16:19], v[14:15], off nt
.LBB0_123:
	s_or_b64 exec, exec, s[12:13]
	v_mov_b32_e32 v13, 0
	v_mov_b32_e32 v14, 0
	v_mov_b32_e32 v15, 0
	s_and_saveexec_b64 s[12:13], vcc
	s_cbranch_execz .LBB0_125
	v_or_b32_e32 v12, 4, v34
	v_ashrrev_i32_e32 v13, 31, v12
	v_lshlrev_b64 v[12:13], 10, v[12:13]
	v_lshl_add_u64 v[12:13], v[36:37], 0, v[12:13]
	global_load_dwordx4 v[12:15], v[12:13], off nt
.LBB0_125:
	s_or_b64 exec, exec, s[12:13]
	v_mov_b32_e32 v20, 0
	v_mov_b32_e32 v24, 0
	v_mov_b32_e32 v25, 0
	v_mov_b32_e32 v26, 0
	v_mov_b32_e32 v27, 0
	s_and_saveexec_b64 s[12:13], vcc
	s_cbranch_execz .LBB0_127
	v_or_b32_e32 v22, 5, v34
	v_ashrrev_i32_e32 v23, 31, v22
	v_lshlrev_b64 v[22:23], 10, v[22:23]
	v_lshl_add_u64 v[22:23], v[36:37], 0, v[22:23]
	global_load_dwordx4 v[24:27], v[22:23], off nt
.LBB0_127:
	s_or_b64 exec, exec, s[12:13]
	v_mov_b32_e32 v21, 0
	v_mov_b32_e32 v22, 0
	v_mov_b32_e32 v23, 0
	s_and_saveexec_b64 s[12:13], vcc
	s_cbranch_execz .LBB0_129
	v_or_b32_e32 v20, 6, v34
	v_ashrrev_i32_e32 v21, 31, v20
	v_lshlrev_b64 v[20:21], 10, v[20:21]
	v_lshl_add_u64 v[20:21], v[36:37], 0, v[20:21]
	global_load_dwordx4 v[20:23], v[20:21], off nt
.LBB0_129:
	s_or_b64 exec, exec, s[12:13]
	v_mov_b32_e32 v28, 0
	v_mov_b32_e32 v29, 0
	v_mov_b32_e32 v30, 0
	v_mov_b32_e32 v31, 0
	s_and_saveexec_b64 s[12:13], vcc
	s_cbranch_execz .LBB0_114
	v_or_b32_e32 v28, 7, v34
	v_ashrrev_i32_e32 v29, 31, v28
	v_lshlrev_b64 v[28:29], 10, v[28:29]
	v_lshl_add_u64 v[28:29], v[36:37], 0, v[28:29]
	global_load_dwordx4 v[28:31], v[28:29], off nt
	s_branch .LBB0_114

.LBB0_133:
	v_ashrrev_i32_e32 v0, 31, v40
	v_lshrrev_b32_e32 v0, 26, v0
	v_add_u32_e32 v0, v40, v0
	v_ashrrev_i32_e32 v41, 6, v0
	v_and_b32_e32 v0, 0xffffffc0, v0
	v_lshlrev_b32_e32 v1, 8, v41
	v_readlane_b32 s40, v252, 10
	v_sub_u32_e32 v0, v40, v0
	v_sub_u32_e32 v32, v38, v1
	v_readlane_b32 s50, v252, 20
	v_readlane_b32 s51, v252, 21
	v_cmp_lt_i32_e32 vcc, -1, v0
	v_lshlrev_b32_e32 v34, 3, v41
	v_lshl_add_u64 v[36:37], v[32:33], 2, s[50:51]
	v_mov_b32_e32 v0, 0
	v_mov_b32_e32 v1, 0
	v_mov_b32_e32 v2, 0
	v_mov_b32_e32 v3, 0
	v_readlane_b32 s41, v252, 11
	v_readlane_b32 s42, v252, 12
	v_readlane_b32 s43, v252, 13
	v_readlane_b32 s44, v252, 14
	v_readlane_b32 s45, v252, 15
	v_readlane_b32 s46, v252, 16
	v_readlane_b32 s47, v252, 17
	v_readlane_b32 s48, v252, 18
	v_readlane_b32 s49, v252, 19
	v_readlane_b32 s52, v252, 22
	v_readlane_b32 s53, v252, 23
	v_readlane_b32 s54, v252, 24
	v_readlane_b32 s55, v252, 25
	s_and_saveexec_b64 s[12:13], vcc
	s_cbranch_execz .LBB0_135
	v_ashrrev_i32_e32 v35, 31, v34
	v_lshlrev_b64 v[0:1], 10, v[34:35]
	v_lshl_add_u64 v[0:1], v[36:37], 0, v[0:1]
	global_load_dwordx4 v[0:3], v[0:1], off nt

.LBB0_155:
	v_ashrrev_i32_e32 v0, 31, v39
	v_lshrrev_b32_e32 v0, 28, v0
	v_add_u32_e32 v0, v39, v0
	v_ashrrev_i32_e32 v1, 4, v0
	v_and_b32_e32 v0, -16, v0
	v_lshlrev_b32_e32 v2, 6, v1
	v_readlane_b32 s40, v252, 10
	v_sub_u32_e32 v0, v39, v0
	v_sub_u32_e32 v32, v38, v2
	v_lshlrev_b32_e32 v34, 3, v1
	v_readlane_b32 s48, v252, 18
	v_readlane_b32 s49, v252, 19
	v_cmp_lt_i32_e64 s[0:1], -1, v0
	v_ashrrev_i32_e32 v35, 31, v34
	v_lshl_add_u64 v[36:37], v[32:33], 2, s[48:49]
	v_mov_b32_e32 v0, 0
	v_mov_b32_e32 v1, 0
	v_mov_b32_e32 v2, 0
	v_mov_b32_e32 v3, 0
	v_readlane_b32 s41, v252, 11
	v_readlane_b32 s42, v252, 12
	v_readlane_b32 s43, v252, 13
	v_readlane_b32 s44, v252, 14
	v_readlane_b32 s45, v252, 15
	v_readlane_b32 s46, v252, 16
	v_readlane_b32 s47, v252, 17
	v_readlane_b32 s50, v252, 20
	v_readlane_b32 s51, v252, 21
	v_readlane_b32 s52, v252, 22
	v_readlane_b32 s53, v252, 23
	v_readlane_b32 s54, v252, 24
	v_readlane_b32 s55, v252, 25
	s_and_saveexec_b64 s[14:15], s[0:1]
	s_cbranch_execz .LBB0_157
	v_lshlrev_b64 v[0:1], 8, v[34:35]
	v_lshl_add_u64 v[0:1], v[36:37], 0, v[0:1]
	global_load_dwordx4 v[0:3], v[0:1], off nt
.LBB0_157:
	s_or_b64 exec, exec, s[14:15]
	v_mov_b32_e32 v4, 0
	v_mov_b32_e32 v8, 0
	v_mov_b32_e32 v9, 0
	v_mov_b32_e32 v10, 0
	v_mov_b32_e32 v11, 0
	s_and_saveexec_b64 s[14:15], s[0:1]
	s_cbranch_execz .LBB0_159
	v_or_b32_e32 v6, 1, v34
	v_ashrrev_i32_e32 v7, 31, v6
	v_lshlrev_b64 v[6:7], 8, v[6:7]
	v_lshl_add_u64 v[6:7], v[36:37], 0, v[6:7]
	global_load_dwordx4 v[8:11], v[6:7], off nt
.LBB0_159:
	s_or_b64 exec, exec, s[14:15]
	v_mov_b32_e32 v5, 0
	v_mov_b32_e32 v6, 0
	v_mov_b32_e32 v7, 0
	s_and_saveexec_b64 s[14:15], s[0:1]
	s_cbranch_execz .LBB0_161
	v_or_b32_e32 v4, 2, v34
	v_ashrrev_i32_e32 v5, 31, v4
	v_lshlrev_b64 v[4:5], 8, v[4:5]
	v_lshl_add_u64 v[4:5], v[36:37], 0, v[4:5]
	global_load_dwordx4 v[4:7], v[4:5], off nt
.LBB0_161:
	s_or_b64 exec, exec, s[14:15]
	v_mov_b32_e32 v12, 0
	v_mov_b32_e32 v16, 0
	v_mov_b32_e32 v17, 0
	v_mov_b32_e32 v18, 0
	v_mov_b32_e32 v19, 0
	s_and_saveexec_b64 s[14:15], s[0:1]
	s_cbranch_execz .LBB0_163
	v_or_b32_e32 v14, 3, v34
	v_ashrrev_i32_e32 v15, 31, v14
	v_lshlrev_b64 v[14:15], 8, v[14:15]
	v_lshl_add_u64 v[14:15], v[36:37], 0, v[14:15]
	global_load_dwordx4 v[16:19], v[14:15], off nt
.LBB0_163:
	s_or_b64 exec, exec, s[14:15]
	v_mov_b32_e32 v13, 0
	v_mov_b32_e32 v14, 0
	v_mov_b32_e32 v15, 0
	s_and_saveexec_b64 s[14:15], s[0:1]
	s_cbranch_execz .LBB0_165
	v_or_b32_e32 v12, 4, v34
	v_ashrrev_i32_e32 v13, 31, v12
	v_lshlrev_b64 v[12:13], 8, v[12:13]
	v_lshl_add_u64 v[12:13], v[36:37], 0, v[12:13]
	global_load_dwordx4 v[12:15], v[12:13], off nt
.LBB0_165:
	s_or_b64 exec, exec, s[14:15]
	v_mov_b32_e32 v20, 0
	v_mov_b32_e32 v24, 0
	v_mov_b32_e32 v25, 0
	v_mov_b32_e32 v26, 0
	v_mov_b32_e32 v27, 0
	s_and_saveexec_b64 s[14:15], s[0:1]
	s_cbranch_execz .LBB0_167
	v_or_b32_e32 v22, 5, v34
	v_ashrrev_i32_e32 v23, 31, v22
	v_lshlrev_b64 v[22:23], 8, v[22:23]
	v_lshl_add_u64 v[22:23], v[36:37], 0, v[22:23]
	global_load_dwordx4 v[24:27], v[22:23], off nt
.LBB0_167:
	s_or_b64 exec, exec, s[14:15]
	v_mov_b32_e32 v21, 0
	v_mov_b32_e32 v22, 0
	v_mov_b32_e32 v23, 0
	s_and_saveexec_b64 s[14:15], s[0:1]
	s_cbranch_execz .LBB0_169
	v_or_b32_e32 v20, 6, v34
	v_ashrrev_i32_e32 v21, 31, v20
	v_lshlrev_b64 v[20:21], 8, v[20:21]
	v_lshl_add_u64 v[20:21], v[36:37], 0, v[20:21]
	global_load_dwordx4 v[20:23], v[20:21], off nt
.LBB0_169:
	s_or_b64 exec, exec, s[14:15]
	v_mov_b32_e32 v28, 0
	v_mov_b32_e32 v29, 0
	v_mov_b32_e32 v30, 0
	v_mov_b32_e32 v31, 0
	s_and_saveexec_b64 s[14:15], s[0:1]
	s_cbranch_execz .LBB0_154
	v_or_b32_e32 v28, 7, v34
	v_ashrrev_i32_e32 v29, 31, v28
	v_lshlrev_b64 v[28:29], 8, v[28:29]
	v_lshl_add_u64 v[28:29], v[36:37], 0, v[28:29]
	global_load_dwordx4 v[28:31], v[28:29], off nt
	s_branch .LBB0_154

.LBB0_173:
	v_ashrrev_i32_e32 v0, 31, v38
	v_lshrrev_b32_e32 v0, 28, v0
	v_add_u32_e32 v0, v38, v0
	v_ashrrev_i32_e32 v1, 4, v0
	v_and_b32_e32 v0, -16, v0
	v_lshlrev_b32_e32 v2, 6, v1
	v_readlane_b32 s40, v252, 10
	v_sub_u32_e32 v0, v38, v0
	v_sub_u32_e32 v32, v62, v2
	v_lshlrev_b32_e32 v34, 3, v1
	v_readlane_b32 s52, v252, 22
	v_readlane_b32 s53, v252, 23
	v_cmp_lt_i32_e64 s[0:1], -1, v0
	v_ashrrev_i32_e32 v35, 31, v34
	v_lshl_add_u64 v[36:37], v[32:33], 2, s[52:53]
	v_mov_b32_e32 v0, 0
	v_mov_b32_e32 v1, 0
	v_mov_b32_e32 v2, 0
	v_mov_b32_e32 v3, 0
	v_readlane_b32 s41, v252, 11
	v_readlane_b32 s42, v252, 12
	v_readlane_b32 s43, v252, 13
	v_readlane_b32 s44, v252, 14
	v_readlane_b32 s45, v252, 15
	v_readlane_b32 s46, v252, 16
	v_readlane_b32 s47, v252, 17
	v_readlane_b32 s48, v252, 18
	v_readlane_b32 s49, v252, 19
	v_readlane_b32 s50, v252, 20
	v_readlane_b32 s51, v252, 21
	v_readlane_b32 s54, v252, 24
	v_readlane_b32 s55, v252, 25
	s_and_saveexec_b64 s[14:15], s[0:1]
	s_cbranch_execz .LBB0_175
	v_lshlrev_b64 v[0:1], 8, v[34:35]
	v_lshl_add_u64 v[0:1], v[36:37], 0, v[0:1]
	global_load_dwordx4 v[0:3], v[0:1], off nt

.LBB0_522:
	v_ashrrev_i32_e32 v0, 31, v38
	v_add_u32_sdwa v0, v38, v0 dst_sel:DWORD dst_unused:UNUSED_PAD src0_sel:DWORD src1_sel:BYTE_3
	v_ashrrev_i32_e32 v39, 8, v0
	v_mul_i32_i24_e32 v40, 0x100, v39
	v_lshlrev_b32_e32 v1, 2, v40
	v_sub_u32_e32 v0, v38, v40
	v_sub_u32_e32 v192, v36, v1
	v_cmp_lt_i32_e32 vcc, -1, v0
	s_waitcnt vmcnt(0)
	v_lshlrev_b32_e32 v34, 3, v39
	v_lshl_add_u64 v[32:33], v[192:193], 2, s[28:29]
	v_mov_b32_e32 v4, 0
	v_mov_b32_e32 v0, 0
	v_mov_b32_e32 v1, 0
	v_mov_b32_e32 v2, 0
	v_mov_b32_e32 v3, 0
	s_and_saveexec_b64 s[34:35], vcc
	s_cbranch_execz .LBB0_524
	v_ashrrev_i32_e32 v35, 31, v34
	v_lshlrev_b64 v[0:1], 12, v[34:35]
	v_lshl_add_u64 v[0:1], v[32:33], 0, v[0:1]
	global_load_dwordx4 v[0:3], v[0:1], off nt
.LBB0_524:
	s_or_b64 exec, exec, s[34:35]
	v_mov_b32_e32 v5, 0
	v_mov_b32_e32 v6, 0
	v_mov_b32_e32 v7, 0
	s_and_saveexec_b64 s[34:35], vcc
	s_cbranch_execz .LBB0_526
	v_or_b32_e32 v4, 1, v34
	v_ashrrev_i32_e32 v5, 31, v4
	v_lshlrev_b64 v[4:5], 12, v[4:5]
	v_lshl_add_u64 v[4:5], v[32:33], 0, v[4:5]
	global_load_dwordx4 v[4:7], v[4:5], off nt
.LBB0_526:
	s_or_b64 exec, exec, s[34:35]
	v_mov_b32_e32 v8, 0
	v_mov_b32_e32 v12, 0
	v_mov_b32_e32 v13, 0
	v_mov_b32_e32 v14, 0
	v_mov_b32_e32 v15, 0
	s_and_saveexec_b64 s[34:35], vcc
	s_cbranch_execz .LBB0_528
	v_or_b32_e32 v10, 2, v34
	v_ashrrev_i32_e32 v11, 31, v10
	v_lshlrev_b64 v[10:11], 12, v[10:11]
	v_lshl_add_u64 v[10:11], v[32:33], 0, v[10:11]
	global_load_dwordx4 v[12:15], v[10:11], off nt
.LBB0_528:
	s_or_b64 exec, exec, s[34:35]
	v_mov_b32_e32 v9, 0
	v_mov_b32_e32 v10, 0
	v_mov_b32_e32 v11, 0
	s_and_saveexec_b64 s[34:35], vcc
	s_cbranch_execz .LBB0_530
	v_or_b32_e32 v8, 3, v34
	v_ashrrev_i32_e32 v9, 31, v8
	v_lshlrev_b64 v[8:9], 12, v[8:9]
	v_lshl_add_u64 v[8:9], v[32:33], 0, v[8:9]
	global_load_dwordx4 v[8:11], v[8:9], off nt
.LBB0_530:
	s_or_b64 exec, exec, s[34:35]
	v_mov_b32_e32 v16, 0
	v_mov_b32_e32 v20, 0
	v_mov_b32_e32 v21, 0
	v_mov_b32_e32 v22, 0
	v_mov_b32_e32 v23, 0
	s_and_saveexec_b64 s[34:35], vcc
	s_cbranch_execz .LBB0_532
	v_or_b32_e32 v18, 4, v34
	v_ashrrev_i32_e32 v19, 31, v18
	v_lshlrev_b64 v[18:19], 12, v[18:19]
	v_lshl_add_u64 v[18:19], v[32:33], 0, v[18:19]
	global_load_dwordx4 v[20:23], v[18:19], off nt
.LBB0_532:
	s_or_b64 exec, exec, s[34:35]
	v_mov_b32_e32 v17, 0
	v_mov_b32_e32 v18, 0
	v_mov_b32_e32 v19, 0
	s_and_saveexec_b64 s[34:35], vcc
	s_cbranch_execz .LBB0_534
	v_or_b32_e32 v16, 5, v34
	v_ashrrev_i32_e32 v17, 31, v16
	v_lshlrev_b64 v[16:17], 12, v[16:17]
	v_lshl_add_u64 v[16:17], v[32:33], 0, v[16:17]
	global_load_dwordx4 v[16:19], v[16:17], off nt
.LBB0_534:
	s_or_b64 exec, exec, s[34:35]
	v_mov_b32_e32 v24, 0
	v_mov_b32_e32 v28, 0
	v_mov_b32_e32 v29, 0
	v_mov_b32_e32 v30, 0
	v_mov_b32_e32 v31, 0
	s_and_saveexec_b64 s[34:35], vcc
	s_cbranch_execz .LBB0_536
	v_or_b32_e32 v26, 6, v34
	v_ashrrev_i32_e32 v27, 31, v26
	v_lshlrev_b64 v[26:27], 12, v[26:27]
	v_lshl_add_u64 v[26:27], v[32:33], 0, v[26:27]
	global_load_dwordx4 v[28:31], v[26:27], off nt
.LBB0_536:
	s_or_b64 exec, exec, s[34:35]
	v_mov_b32_e32 v25, 0
	v_mov_b32_e32 v26, 0
	v_mov_b32_e32 v27, 0
	s_and_saveexec_b64 s[34:35], vcc
	s_cbranch_execz .LBB0_521
	v_or_b32_e32 v24, 7, v34
	v_ashrrev_i32_e32 v25, 31, v24
	v_lshlrev_b64 v[24:25], 12, v[24:25]
	v_lshl_add_u64 v[24:25], v[32:33], 0, v[24:25]
	global_load_dwordx4 v[24:27], v[24:25], off nt
	s_branch .LBB0_521

.LBB0_556:
	s_or_b64 exec, exec, s[0:1]
	v_cmp_lt_i32_e64 s[0:1], -1, v192
	v_lshlrev_b32_e32 v32, 3, v39
	s_waitcnt vmcnt(0)
	v_lshl_add_u64 v[34:35], v[192:193], 2, s[40:41]
	v_mov_b32_e32 v4, 0
	v_mov_b32_e32 v0, 0
	v_mov_b32_e32 v1, 0
	v_mov_b32_e32 v2, 0
	v_mov_b32_e32 v3, 0
	s_and_saveexec_b64 s[28:29], s[0:1]
	s_cbranch_execz .LBB0_559
	v_mad_i64_i32 v[0:1], s[30:31], v32, s78, v[34:35]
	global_load_dwordx4 v[0:3], v[0:1], off nt
	s_and_b64 vcc, exec, s[74:75]
	s_cbranch_vccnz .LBB0_559
	v_ashrrev_i32_e32 v33, 31, v32
	v_lshl_add_u64 v[6:7], v[32:33], 2, s[86:87]
	global_load_dword v50, v[6:7], off
.LBB0_559:
	s_or_b64 exec, exec, s[28:29]
	v_mov_b32_e32 v5, 0
	v_mov_b32_e32 v6, 0
	v_mov_b32_e32 v7, 0
	s_and_saveexec_b64 s[28:29], s[0:1]
	s_cbranch_execz .LBB0_562
	v_or_b32_e32 v8, 1, v32
	v_mad_i64_i32 v[4:5], s[30:31], v8, s78, v[34:35]
	global_load_dwordx4 v[4:7], v[4:5], off nt
	s_and_b64 vcc, exec, s[74:75]
	s_cbranch_vccnz .LBB0_562
	v_ashrrev_i32_e32 v9, 31, v8
	v_lshl_add_u64 v[8:9], v[8:9], 2, s[86:87]
	global_load_dword v51, v[8:9], off
.LBB0_562:
	s_or_b64 exec, exec, s[28:29]
	v_mov_b32_e32 v8, 0
	v_mov_b32_e32 v12, 0
	v_mov_b32_e32 v13, 0
	v_mov_b32_e32 v14, 0
	v_mov_b32_e32 v15, 0
	s_and_saveexec_b64 s[28:29], s[0:1]
	s_cbranch_execz .LBB0_565
	v_or_b32_e32 v10, 2, v32
	v_mad_i64_i32 v[12:13], s[30:31], v10, s78, v[34:35]
	global_load_dwordx4 v[12:15], v[12:13], off nt
	s_and_b64 vcc, exec, s[74:75]
	s_cbranch_vccnz .LBB0_565
	v_ashrrev_i32_e32 v11, 31, v10
	v_lshl_add_u64 v[10:11], v[10:11], 2, s[86:87]
	global_load_dword v52, v[10:11], off
.LBB0_565:
	s_or_b64 exec, exec, s[28:29]
	v_mov_b32_e32 v9, 0
	v_mov_b32_e32 v10, 0
	v_mov_b32_e32 v11, 0
	s_and_saveexec_b64 s[28:29], s[0:1]
	s_cbranch_execz .LBB0_568
	v_or_b32_e32 v16, 3, v32
	v_mad_i64_i32 v[8:9], s[30:31], v16, s78, v[34:35]
	global_load_dwordx4 v[8:11], v[8:9], off nt
	s_and_b64 vcc, exec, s[74:75]
	s_cbranch_vccnz .LBB0_568
	v_ashrrev_i32_e32 v17, 31, v16
	v_lshl_add_u64 v[16:17], v[16:17], 2, s[86:87]
	global_load_dword v53, v[16:17], off
.LBB0_568:
	s_or_b64 exec, exec, s[28:29]
	v_mov_b32_e32 v16, 0
	v_mov_b32_e32 v20, 0
	v_mov_b32_e32 v21, 0
	v_mov_b32_e32 v22, 0
	v_mov_b32_e32 v23, 0
	s_and_saveexec_b64 s[28:29], s[0:1]
	s_cbranch_execz .LBB0_571
	v_or_b32_e32 v18, 4, v32
	v_mad_i64_i32 v[20:21], s[30:31], v18, s78, v[34:35]
	global_load_dwordx4 v[20:23], v[20:21], off nt
	s_and_b64 vcc, exec, s[74:75]
	s_cbranch_vccnz .LBB0_571
	v_ashrrev_i32_e32 v19, 31, v18
	v_lshl_add_u64 v[18:19], v[18:19], 2, s[86:87]
	global_load_dword v54, v[18:19], off
.LBB0_571:
	s_or_b64 exec, exec, s[28:29]
	v_mov_b32_e32 v17, 0
	v_mov_b32_e32 v18, 0
	v_mov_b32_e32 v19, 0
	s_and_saveexec_b64 s[28:29], s[0:1]
	s_cbranch_execz .LBB0_574
	v_or_b32_e32 v24, 5, v32
	v_mad_i64_i32 v[16:17], s[30:31], v24, s78, v[34:35]
	global_load_dwordx4 v[16:19], v[16:17], off nt
	s_and_b64 vcc, exec, s[74:75]
	s_cbranch_vccnz .LBB0_574
	v_ashrrev_i32_e32 v25, 31, v24
	v_lshl_add_u64 v[24:25], v[24:25], 2, s[86:87]
	global_load_dword v55, v[24:25], off
.LBB0_574:
	s_or_b64 exec, exec, s[28:29]
	v_mov_b32_e32 v24, 0
	v_mov_b32_e32 v28, 0
	v_mov_b32_e32 v29, 0
	v_mov_b32_e32 v30, 0
	v_mov_b32_e32 v31, 0
	s_and_saveexec_b64 s[28:29], s[0:1]
	s_cbranch_execz .LBB0_577
	v_or_b32_e32 v26, 6, v32
	v_mad_i64_i32 v[28:29], s[30:31], v26, s78, v[34:35]
	global_load_dwordx4 v[28:31], v[28:29], off nt
	s_and_b64 vcc, exec, s[74:75]
	s_cbranch_vccnz .LBB0_577
	v_ashrrev_i32_e32 v27, 31, v26
	v_lshl_add_u64 v[26:27], v[26:27], 2, s[86:87]
	global_load_dword v56, v[26:27], off
.LBB0_577:
	s_or_b64 exec, exec, s[28:29]
	v_mov_b32_e32 v25, 0
	v_mov_b32_e32 v26, 0
	v_mov_b32_e32 v27, 0
	s_and_saveexec_b64 s[28:29], s[0:1]
	s_cbranch_execz .LBB0_541
	v_or_b32_e32 v32, 7, v32
	v_mad_i64_i32 v[24:25], s[0:1], v32, s78, v[34:35]
	global_load_dwordx4 v[24:27], v[24:25], off nt
	s_and_b64 vcc, exec, s[74:75]
	s_cbranch_vccnz .LBB0_541
	v_ashrrev_i32_e32 v33, 31, v32
	v_lshl_add_u64 v[32:33], v[32:33], 2, s[86:87]
	global_load_dword v57, v[32:33], off
	s_waitcnt vmcnt(0)
	v_mul_f32_e32 v2, v2, v50
	v_mul_f32_e32 v3, v3, v50
	v_mul_f32_e32 v0, v0, v50
	v_mul_f32_e32 v1, v1, v50
	v_mul_f32_e32 v6, v6, v51
	v_mul_f32_e32 v7, v7, v51
	v_mul_f32_e32 v4, v4, v51
	v_mul_f32_e32 v5, v5, v51
	v_mul_f32_e32 v14, v14, v52
	v_mul_f32_e32 v15, v15, v52
	v_mul_f32_e32 v12, v12, v52
	v_mul_f32_e32 v13, v13, v52
	v_mul_f32_e32 v10, v10, v53
	v_mul_f32_e32 v11, v11, v53
	v_mul_f32_e32 v8, v8, v53
	v_mul_f32_e32 v9, v9, v53
	v_mul_f32_e32 v22, v22, v54
	v_mul_f32_e32 v23, v23, v54
	v_mul_f32_e32 v20, v20, v54
	v_mul_f32_e32 v21, v21, v54
	v_mul_f32_e32 v18, v18, v55
	v_mul_f32_e32 v19, v19, v55
	v_mul_f32_e32 v16, v16, v55
	v_mul_f32_e32 v17, v17, v55
	v_mul_f32_e32 v30, v30, v56
	v_mul_f32_e32 v31, v31, v56
	v_mul_f32_e32 v28, v28, v56
	v_mul_f32_e32 v29, v29, v56
	v_mul_f32_e32 v26, v26, v57
	v_mul_f32_e32 v27, v27, v57
	v_mul_f32_e32 v24, v24, v57
	v_mul_f32_e32 v25, v25, v57
	s_branch .LBB0_541

.LBB0_583:
	v_mul_hi_i32 v0, v34, s54
	v_lshrrev_b32_e32 v1, 31, v0
	v_ashrrev_i32_e32 v0, 4, v0
	v_add_u32_e32 v2, v0, v1
	s_movk_i32 s0, 0xffa0
	v_mad_u64_u32 v[0:1], s[0:1], v2, s0, v[34:35]
	s_movk_i32 s0, 0xfe80
	s_nop 0
	v_mad_u64_u32 v[36:37], s[0:1], v2, s0, v[32:33]
	v_lshlrev_b32_e32 v38, 3, v2
	v_mov_b32_e32 v37, v193
	v_cmp_lt_i32_e64 s[0:1], -1, v0
	v_lshl_add_u64 v[40:41], v[36:37], 2, s[42:43]
	v_mov_b32_e32 v0, 0
	v_ashrrev_i32_e32 v39, 31, v38
	v_mov_b32_e32 v4, 0
	v_mov_b32_e32 v5, 0
	v_mov_b32_e32 v6, 0
	v_mov_b32_e32 v7, 0
	s_and_saveexec_b64 s[28:29], s[0:1]
	s_cbranch_execz .LBB0_586
	v_mad_i64_i32 v[2:3], s[34:35], v38, s33, v[40:41]
	global_load_dwordx4 v[4:7], v[2:3], off nt
	s_and_b64 vcc, exec, s[4:5]
	s_cbranch_vccnz .LBB0_586
	v_lshl_add_u64 v[2:3], v[38:39], 2, s[90:91]
	global_load_dword v50, v[2:3], off offset:1024
.LBB0_586:
	s_or_b64 exec, exec, s[28:29]
	v_mov_b32_e32 v1, 0
	v_mov_b32_e32 v2, 0
	v_mov_b32_e32 v3, 0
	s_and_saveexec_b64 s[28:29], s[0:1]
	s_cbranch_execz .LBB0_589
	v_or_b32_e32 v0, 1, v38
	v_mad_i64_i32 v[0:1], s[34:35], v0, s33, v[40:41]
	global_load_dwordx4 v[0:3], v[0:1], off nt
	s_and_b64 vcc, exec, s[4:5]
	s_cbranch_vccnz .LBB0_589
	v_lshl_add_u64 v[8:9], v[38:39], 2, s[90:91]
	global_load_dword v51, v[8:9], off offset:1028
.LBB0_589:
	s_or_b64 exec, exec, s[28:29]
	v_mov_b32_e32 v8, 0
	v_mov_b32_e32 v12, 0
	v_mov_b32_e32 v13, 0
	v_mov_b32_e32 v14, 0
	v_mov_b32_e32 v15, 0
	s_and_saveexec_b64 s[28:29], s[0:1]
	s_cbranch_execz .LBB0_592
	v_or_b32_e32 v9, 2, v38
	v_mad_i64_i32 v[10:11], s[34:35], v9, s33, v[40:41]
	global_load_dwordx4 v[12:15], v[10:11], off nt
	s_and_b64 vcc, exec, s[4:5]
	s_cbranch_vccnz .LBB0_592
	v_lshl_add_u64 v[10:11], v[38:39], 2, s[90:91]
	global_load_dword v52, v[10:11], off offset:1032
.LBB0_592:
	s_or_b64 exec, exec, s[28:29]
	v_mov_b32_e32 v9, 0
	v_mov_b32_e32 v10, 0
	v_mov_b32_e32 v11, 0
	s_and_saveexec_b64 s[28:29], s[0:1]
	s_cbranch_execz .LBB0_595
	v_or_b32_e32 v8, 3, v38
	v_mad_i64_i32 v[8:9], s[34:35], v8, s33, v[40:41]
	global_load_dwordx4 v[8:11], v[8:9], off nt
	s_and_b64 vcc, exec, s[4:5]
	s_cbranch_vccnz .LBB0_595
	v_lshl_add_u64 v[16:17], v[38:39], 2, s[90:91]
	global_load_dword v53, v[16:17], off offset:1036
.LBB0_595:
	s_or_b64 exec, exec, s[28:29]
	v_mov_b32_e32 v16, 0
	v_mov_b32_e32 v20, 0
	v_mov_b32_e32 v21, 0
	v_mov_b32_e32 v22, 0
	v_mov_b32_e32 v23, 0
	s_and_saveexec_b64 s[28:29], s[0:1]
	s_cbranch_execz .LBB0_598
	v_or_b32_e32 v17, 4, v38
	v_mad_i64_i32 v[18:19], s[34:35], v17, s33, v[40:41]
	global_load_dwordx4 v[20:23], v[18:19], off nt
	s_and_b64 vcc, exec, s[4:5]
	s_cbranch_vccnz .LBB0_598
	v_lshl_add_u64 v[18:19], v[38:39], 2, s[90:91]
	global_load_dword v54, v[18:19], off offset:1040
.LBB0_598:
	s_or_b64 exec, exec, s[28:29]
	v_mov_b32_e32 v17, 0
	v_mov_b32_e32 v18, 0
	v_mov_b32_e32 v19, 0
	s_and_saveexec_b64 s[28:29], s[0:1]
	s_cbranch_execz .LBB0_601
	v_or_b32_e32 v16, 5, v38
	v_mad_i64_i32 v[16:17], s[34:35], v16, s33, v[40:41]
	global_load_dwordx4 v[16:19], v[16:17], off nt
	s_and_b64 vcc, exec, s[4:5]
	s_cbranch_vccnz .LBB0_601
	v_lshl_add_u64 v[24:25], v[38:39], 2, s[90:91]
	global_load_dword v55, v[24:25], off offset:1044
.LBB0_601:
	s_or_b64 exec, exec, s[28:29]
	v_mov_b32_e32 v24, 0
	v_mov_b32_e32 v28, 0
	v_mov_b32_e32 v29, 0
	v_mov_b32_e32 v30, 0
	v_mov_b32_e32 v31, 0
	s_and_saveexec_b64 s[28:29], s[0:1]
	s_cbranch_execz .LBB0_604
	v_or_b32_e32 v25, 6, v38
	v_mad_i64_i32 v[26:27], s[34:35], v25, s33, v[40:41]
	global_load_dwordx4 v[28:31], v[26:27], off nt
	s_and_b64 vcc, exec, s[4:5]
	s_cbranch_vccnz .LBB0_604
	v_lshl_add_u64 v[26:27], v[38:39], 2, s[90:91]
	global_load_dword v56, v[26:27], off offset:1048
.LBB0_604:
	s_or_b64 exec, exec, s[28:29]
	v_mov_b32_e32 v25, 0
	v_mov_b32_e32 v26, 0
	v_mov_b32_e32 v27, 0
	s_and_saveexec_b64 s[28:29], s[0:1]
	s_cbranch_execz .LBB0_582
	v_or_b32_e32 v24, 7, v38
	v_mad_i64_i32 v[24:25], s[0:1], v24, s33, v[40:41]
	global_load_dwordx4 v[24:27], v[24:25], off nt
	s_and_b64 vcc, exec, s[4:5]
	s_cbranch_vccnz .LBB0_582
	v_lshl_add_u64 v[40:41], v[38:39], 2, s[90:91]
	global_load_dword v57, v[40:41], off offset:1052
	s_waitcnt vmcnt(0)
	v_mul_f32_e32 v6, v6, v50
	v_mul_f32_e32 v7, v7, v50
	v_mul_f32_e32 v4, v4, v50
	v_mul_f32_e32 v5, v5, v50
	v_mul_f32_e32 v2, v2, v51
	v_mul_f32_e32 v3, v3, v51
	v_mul_f32_e32 v0, v0, v51
	v_mul_f32_e32 v1, v1, v51
	v_mul_f32_e32 v14, v14, v52
	v_mul_f32_e32 v15, v15, v52
	v_mul_f32_e32 v12, v12, v52
	v_mul_f32_e32 v13, v13, v52
	v_mul_f32_e32 v10, v10, v53
	v_mul_f32_e32 v11, v11, v53
	v_mul_f32_e32 v8, v8, v53
	v_mul_f32_e32 v9, v9, v53
	v_mul_f32_e32 v22, v22, v54
	v_mul_f32_e32 v23, v23, v54
	v_mul_f32_e32 v20, v20, v54
	v_mul_f32_e32 v21, v21, v54
	v_mul_f32_e32 v18, v18, v55
	v_mul_f32_e32 v19, v19, v55
	v_mul_f32_e32 v16, v16, v55
	v_mul_f32_e32 v17, v17, v55
	v_mul_f32_e32 v30, v30, v56
	v_mul_f32_e32 v31, v31, v56
	v_mul_f32_e32 v28, v28, v56
	v_mul_f32_e32 v29, v29, v56
	v_mul_f32_e32 v26, v26, v57
	v_mul_f32_e32 v27, v27, v57
	v_mul_f32_e32 v24, v24, v57
	v_mul_f32_e32 v25, v25, v57
	s_branch .LBB0_582

.LBB0_610:
	v_ashrrev_i32_e32 v0, 31, v37
	v_lshrrev_b32_e32 v0, 25, v0
	v_add_u32_e32 v0, v37, v0
	v_ashrrev_i32_e32 v1, 7, v0
	v_and_b32_e32 v0, 0xffffff80, v0
	v_lshlrev_b32_e32 v2, 9, v1
	v_sub_u32_e32 v0, v37, v0
	v_sub_u32_e32 v192, v36, v2
	v_lshlrev_b32_e32 v32, 3, v1
	v_cmp_lt_i32_e64 s[0:1], -1, v0
	s_waitcnt vmcnt(0)
	v_lshl_add_u64 v[34:35], v[192:193], 2, s[44:45]
	v_mov_b32_e32 v4, 0
	v_ashrrev_i32_e32 v33, 31, v32
	v_mov_b32_e32 v0, 0
	v_mov_b32_e32 v1, 0
	v_mov_b32_e32 v2, 0
	v_mov_b32_e32 v3, 0
	s_and_saveexec_b64 s[28:29], s[0:1]
	s_cbranch_execz .LBB0_613
	v_lshlrev_b64 v[0:1], 11, v[32:33]
	v_lshl_add_u64 v[0:1], v[34:35], 0, v[0:1]
	global_load_dwordx4 v[0:3], v[0:1], off nt
	s_and_b64 vcc, exec, s[6:7]
	s_cbranch_vccnz .LBB0_613
	v_lshl_add_u64 v[6:7], v[32:33], 2, s[92:93]
	global_load_dword v50, v[6:7], off offset:512
.LBB0_613:
	s_or_b64 exec, exec, s[28:29]
	v_mov_b32_e32 v5, 0
	v_mov_b32_e32 v6, 0
	v_mov_b32_e32 v7, 0
	s_and_saveexec_b64 s[28:29], s[0:1]
	s_cbranch_execz .LBB0_616
	v_or_b32_e32 v4, 1, v32
	v_ashrrev_i32_e32 v5, 31, v4
	v_lshlrev_b64 v[4:5], 11, v[4:5]
	v_lshl_add_u64 v[4:5], v[34:35], 0, v[4:5]
	global_load_dwordx4 v[4:7], v[4:5], off nt
	s_and_b64 vcc, exec, s[6:7]
	s_cbranch_vccnz .LBB0_616
	v_lshl_add_u64 v[8:9], v[32:33], 2, s[92:93]
	global_load_dword v51, v[8:9], off offset:516
.LBB0_616:
	s_or_b64 exec, exec, s[28:29]
	v_mov_b32_e32 v8, 0
	v_mov_b32_e32 v12, 0
	v_mov_b32_e32 v13, 0
	v_mov_b32_e32 v14, 0
	v_mov_b32_e32 v15, 0
	s_and_saveexec_b64 s[28:29], s[0:1]
	s_cbranch_execz .LBB0_619
	v_or_b32_e32 v10, 2, v32
	v_ashrrev_i32_e32 v11, 31, v10
	v_lshlrev_b64 v[10:11], 11, v[10:11]
	v_lshl_add_u64 v[10:11], v[34:35], 0, v[10:11]
	global_load_dwordx4 v[12:15], v[10:11], off nt
	s_and_b64 vcc, exec, s[6:7]
	s_cbranch_vccnz .LBB0_619
	v_lshl_add_u64 v[10:11], v[32:33], 2, s[92:93]
	global_load_dword v52, v[10:11], off offset:520
.LBB0_619:
	s_or_b64 exec, exec, s[28:29]
	v_mov_b32_e32 v9, 0
	v_mov_b32_e32 v10, 0
	v_mov_b32_e32 v11, 0
	s_and_saveexec_b64 s[28:29], s[0:1]
	s_cbranch_execz .LBB0_622
	v_or_b32_e32 v8, 3, v32
	v_ashrrev_i32_e32 v9, 31, v8
	v_lshlrev_b64 v[8:9], 11, v[8:9]
	v_lshl_add_u64 v[8:9], v[34:35], 0, v[8:9]
	global_load_dwordx4 v[8:11], v[8:9], off nt
	s_and_b64 vcc, exec, s[6:7]
	s_cbranch_vccnz .LBB0_622
	v_lshl_add_u64 v[16:17], v[32:33], 2, s[92:93]
	global_load_dword v53, v[16:17], off offset:524
.LBB0_622:
	s_or_b64 exec, exec, s[28:29]
	v_mov_b32_e32 v16, 0
	v_mov_b32_e32 v20, 0
	v_mov_b32_e32 v21, 0
	v_mov_b32_e32 v22, 0
	v_mov_b32_e32 v23, 0
	s_and_saveexec_b64 s[28:29], s[0:1]
	s_cbranch_execz .LBB0_625
	v_or_b32_e32 v18, 4, v32
	v_ashrrev_i32_e32 v19, 31, v18
	v_lshlrev_b64 v[18:19], 11, v[18:19]
	v_lshl_add_u64 v[18:19], v[34:35], 0, v[18:19]
	global_load_dwordx4 v[20:23], v[18:19], off nt
	s_and_b64 vcc, exec, s[6:7]
	s_cbranch_vccnz .LBB0_625
	v_lshl_add_u64 v[18:19], v[32:33], 2, s[92:93]
	global_load_dword v54, v[18:19], off offset:528
.LBB0_625:
	s_or_b64 exec, exec, s[28:29]
	v_mov_b32_e32 v17, 0
	v_mov_b32_e32 v18, 0
	v_mov_b32_e32 v19, 0
	s_and_saveexec_b64 s[28:29], s[0:1]
	s_cbranch_execz .LBB0_628
	v_or_b32_e32 v16, 5, v32
	v_ashrrev_i32_e32 v17, 31, v16
	v_lshlrev_b64 v[16:17], 11, v[16:17]
	v_lshl_add_u64 v[16:17], v[34:35], 0, v[16:17]
	global_load_dwordx4 v[16:19], v[16:17], off nt
	s_and_b64 vcc, exec, s[6:7]
	s_cbranch_vccnz .LBB0_628
	v_lshl_add_u64 v[24:25], v[32:33], 2, s[92:93]
	global_load_dword v55, v[24:25], off offset:532
.LBB0_628:
	s_or_b64 exec, exec, s[28:29]
	v_mov_b32_e32 v24, 0
	v_mov_b32_e32 v28, 0
	v_mov_b32_e32 v29, 0
	v_mov_b32_e32 v30, 0
	v_mov_b32_e32 v31, 0
	s_and_saveexec_b64 s[28:29], s[0:1]
	s_cbranch_execz .LBB0_631
	v_or_b32_e32 v26, 6, v32
	v_ashrrev_i32_e32 v27, 31, v26
	v_lshlrev_b64 v[26:27], 11, v[26:27]
	v_lshl_add_u64 v[26:27], v[34:35], 0, v[26:27]
	global_load_dwordx4 v[28:31], v[26:27], off nt
	s_and_b64 vcc, exec, s[6:7]
	s_cbranch_vccnz .LBB0_631
	v_lshl_add_u64 v[26:27], v[32:33], 2, s[92:93]
	global_load_dword v56, v[26:27], off offset:536
.LBB0_631:
	s_or_b64 exec, exec, s[28:29]
	v_mov_b32_e32 v25, 0
	v_mov_b32_e32 v26, 0
	v_mov_b32_e32 v27, 0
	s_and_saveexec_b64 s[28:29], s[0:1]
	s_cbranch_execz .LBB0_609
	v_or_b32_e32 v24, 7, v32
	v_ashrrev_i32_e32 v25, 31, v24
	v_lshlrev_b64 v[24:25], 11, v[24:25]
	v_lshl_add_u64 v[24:25], v[34:35], 0, v[24:25]
	global_load_dwordx4 v[24:27], v[24:25], off nt
	s_and_b64 vcc, exec, s[6:7]
	s_cbranch_vccnz .LBB0_609
	v_lshl_add_u64 v[34:35], v[32:33], 2, s[92:93]
	global_load_dword v57, v[34:35], off offset:540
	s_waitcnt vmcnt(0)
	v_mul_f32_e32 v2, v2, v50
	v_mul_f32_e32 v3, v3, v50
	v_mul_f32_e32 v0, v0, v50
	v_mul_f32_e32 v1, v1, v50
	v_mul_f32_e32 v6, v6, v51
	v_mul_f32_e32 v7, v7, v51
	v_mul_f32_e32 v4, v4, v51
	v_mul_f32_e32 v5, v5, v51
	v_mul_f32_e32 v14, v14, v52
	v_mul_f32_e32 v15, v15, v52
	v_mul_f32_e32 v12, v12, v52
	v_mul_f32_e32 v13, v13, v52
	v_mul_f32_e32 v10, v10, v53
	v_mul_f32_e32 v11, v11, v53
	v_mul_f32_e32 v8, v8, v53
	v_mul_f32_e32 v9, v9, v53
	v_mul_f32_e32 v22, v22, v54
	v_mul_f32_e32 v23, v23, v54
	v_mul_f32_e32 v20, v20, v54
	v_mul_f32_e32 v21, v21, v54
	v_mul_f32_e32 v18, v18, v55
	v_mul_f32_e32 v19, v19, v55
	v_mul_f32_e32 v16, v16, v55
	v_mul_f32_e32 v17, v17, v55
	v_mul_f32_e32 v30, v30, v56
	v_mul_f32_e32 v31, v31, v56
	v_mul_f32_e32 v28, v28, v56
	v_mul_f32_e32 v29, v29, v56
	v_mul_f32_e32 v26, v26, v57
	v_mul_f32_e32 v27, v27, v57
	v_mul_f32_e32 v24, v24, v57
	v_mul_f32_e32 v25, v25, v57
	s_branch .LBB0_609

.LBB0_637:
	v_ashrrev_i32_e32 v0, 31, v40
	v_lshrrev_b32_e32 v0, 26, v0
	v_add_u32_e32 v0, v40, v0
	v_ashrrev_i32_e32 v41, 6, v0
	v_and_b32_e32 v0, 0xffffffc0, v0
	v_lshlrev_b32_e32 v1, 8, v41
	v_sub_u32_e32 v0, v40, v0
	v_sub_u32_e32 v192, v39, v1
	v_cmp_lt_i32_e32 vcc, -1, v0
	s_waitcnt vmcnt(0)
	v_lshlrev_b32_e32 v34, 3, v41
	v_lshl_add_u64 v[32:33], v[192:193], 2, s[46:47]
	v_mov_b32_e32 v4, 0
	v_mov_b32_e32 v0, 0
	v_mov_b32_e32 v1, 0
	v_mov_b32_e32 v2, 0
	v_mov_b32_e32 v3, 0
	s_and_saveexec_b64 s[26:27], vcc
	s_cbranch_execz .LBB0_639
	v_ashrrev_i32_e32 v35, 31, v34
	v_lshlrev_b64 v[0:1], 10, v[34:35]
	v_lshl_add_u64 v[0:1], v[32:33], 0, v[0:1]
	global_load_dwordx4 v[0:3], v[0:1], off nt
.LBB0_639:
	s_or_b64 exec, exec, s[26:27]
	v_mov_b32_e32 v5, 0
	v_mov_b32_e32 v6, 0
	v_mov_b32_e32 v7, 0
	s_and_saveexec_b64 s[26:27], vcc
	s_cbranch_execz .LBB0_641
	v_or_b32_e32 v4, 1, v34
	v_ashrrev_i32_e32 v5, 31, v4
	v_lshlrev_b64 v[4:5], 10, v[4:5]
	v_lshl_add_u64 v[4:5], v[32:33], 0, v[4:5]
	global_load_dwordx4 v[4:7], v[4:5], off nt
.LBB0_641:
	s_or_b64 exec, exec, s[26:27]
	v_mov_b32_e32 v8, 0
	v_mov_b32_e32 v12, 0
	v_mov_b32_e32 v13, 0
	v_mov_b32_e32 v14, 0
	v_mov_b32_e32 v15, 0
	s_and_saveexec_b64 s[26:27], vcc
	s_cbranch_execz .LBB0_643
	v_or_b32_e32 v10, 2, v34
	v_ashrrev_i32_e32 v11, 31, v10
	v_lshlrev_b64 v[10:11], 10, v[10:11]
	v_lshl_add_u64 v[10:11], v[32:33], 0, v[10:11]
	global_load_dwordx4 v[12:15], v[10:11], off nt
.LBB0_643:
	s_or_b64 exec, exec, s[26:27]
	v_mov_b32_e32 v9, 0
	v_mov_b32_e32 v10, 0
	v_mov_b32_e32 v11, 0
	s_and_saveexec_b64 s[26:27], vcc
	s_cbranch_execz .LBB0_645
	v_or_b32_e32 v8, 3, v34
	v_ashrrev_i32_e32 v9, 31, v8
	v_lshlrev_b64 v[8:9], 10, v[8:9]
	v_lshl_add_u64 v[8:9], v[32:33], 0, v[8:9]
	global_load_dwordx4 v[8:11], v[8:9], off nt
.LBB0_645:
	s_or_b64 exec, exec, s[26:27]
	v_mov_b32_e32 v16, 0
	v_mov_b32_e32 v20, 0
	v_mov_b32_e32 v21, 0
	v_mov_b32_e32 v22, 0
	v_mov_b32_e32 v23, 0
	s_and_saveexec_b64 s[26:27], vcc
	s_cbranch_execz .LBB0_647
	v_or_b32_e32 v18, 4, v34
	v_ashrrev_i32_e32 v19, 31, v18
	v_lshlrev_b64 v[18:19], 10, v[18:19]
	v_lshl_add_u64 v[18:19], v[32:33], 0, v[18:19]
	global_load_dwordx4 v[20:23], v[18:19], off nt
.LBB0_647:
	s_or_b64 exec, exec, s[26:27]
	v_mov_b32_e32 v17, 0
	v_mov_b32_e32 v18, 0
	v_mov_b32_e32 v19, 0
	s_and_saveexec_b64 s[26:27], vcc
	s_cbranch_execz .LBB0_649
	v_or_b32_e32 v16, 5, v34
	v_ashrrev_i32_e32 v17, 31, v16
	v_lshlrev_b64 v[16:17], 10, v[16:17]
	v_lshl_add_u64 v[16:17], v[32:33], 0, v[16:17]
	global_load_dwordx4 v[16:19], v[16:17], off nt
.LBB0_649:
	s_or_b64 exec, exec, s[26:27]
	v_mov_b32_e32 v24, 0
	v_mov_b32_e32 v28, 0
	v_mov_b32_e32 v29, 0
	v_mov_b32_e32 v30, 0
	v_mov_b32_e32 v31, 0
	s_and_saveexec_b64 s[26:27], vcc
	s_cbranch_execz .LBB0_651
	v_or_b32_e32 v26, 6, v34
	v_ashrrev_i32_e32 v27, 31, v26
	v_lshlrev_b64 v[26:27], 10, v[26:27]
	v_lshl_add_u64 v[26:27], v[32:33], 0, v[26:27]
	global_load_dwordx4 v[28:31], v[26:27], off nt
.LBB0_651:
	s_or_b64 exec, exec, s[26:27]
	v_mov_b32_e32 v25, 0
	v_mov_b32_e32 v26, 0
	v_mov_b32_e32 v27, 0
	s_and_saveexec_b64 s[26:27], vcc
	s_cbranch_execz .LBB0_636
	v_or_b32_e32 v24, 7, v34
	v_ashrrev_i32_e32 v25, 31, v24
	v_lshlrev_b64 v[24:25], 10, v[24:25]
	v_lshl_add_u64 v[24:25], v[32:33], 0, v[24:25]
	global_load_dwordx4 v[24:27], v[24:25], off nt
	s_branch .LBB0_636

.LBB0_657:
	v_ashrrev_i32_e32 v0, 31, v38
	v_lshrrev_b32_e32 v0, 26, v0
	v_add_u32_e32 v0, v38, v0
	v_ashrrev_i32_e32 v39, 6, v0
	v_and_b32_e32 v0, 0xffffffc0, v0
	v_lshlrev_b32_e32 v1, 8, v39
	v_sub_u32_e32 v0, v38, v0
	v_sub_u32_e32 v192, v36, v1
	v_cmp_lt_i32_e32 vcc, -1, v0
	v_lshlrev_b32_e32 v34, 3, v39
	v_lshl_add_u64 v[32:33], v[192:193], 2, s[48:49]
	v_mov_b32_e32 v4, 0
	v_mov_b32_e32 v0, 0
	v_mov_b32_e32 v1, 0
	v_mov_b32_e32 v2, 0
	v_mov_b32_e32 v3, 0
	s_and_saveexec_b64 s[26:27], vcc
	s_cbranch_execz .LBB0_659
	v_ashrrev_i32_e32 v35, 31, v34
	v_lshlrev_b64 v[0:1], 10, v[34:35]
	v_lshl_add_u64 v[0:1], v[32:33], 0, v[0:1]
	global_load_dwordx4 v[0:3], v[0:1], off nt

.LBB0_677:
	v_ashrrev_i32_e32 v0, 31, v37
	v_lshrrev_b32_e32 v0, 28, v0
	v_add_u32_e32 v0, v37, v0
	v_ashrrev_i32_e32 v1, 4, v0
	v_and_b32_e32 v0, -16, v0
	v_lshlrev_b32_e32 v2, 6, v1
	v_sub_u32_e32 v0, v37, v0
	v_sub_u32_e32 v192, v36, v2
	v_lshlrev_b32_e32 v32, 3, v1
	v_cmp_lt_i32_e32 vcc, -1, v0
	s_waitcnt vmcnt(0)
	v_lshl_add_u64 v[34:35], v[192:193], 2, s[50:51]
	v_mov_b32_e32 v4, 0
	v_ashrrev_i32_e32 v33, 31, v32
	v_mov_b32_e32 v0, 0
	v_mov_b32_e32 v1, 0
	v_mov_b32_e32 v2, 0
	v_mov_b32_e32 v3, 0
	s_and_saveexec_b64 s[26:27], vcc
	s_cbranch_execz .LBB0_679
	v_lshlrev_b64 v[0:1], 8, v[32:33]
	v_lshl_add_u64 v[0:1], v[34:35], 0, v[0:1]
	global_load_dwordx4 v[0:3], v[0:1], off nt
.LBB0_679:
	s_or_b64 exec, exec, s[26:27]
	v_mov_b32_e32 v5, 0
	v_mov_b32_e32 v6, 0
	v_mov_b32_e32 v7, 0
	s_and_saveexec_b64 s[26:27], vcc
	s_cbranch_execz .LBB0_681
	v_or_b32_e32 v4, 1, v32
	v_ashrrev_i32_e32 v5, 31, v4
	v_lshlrev_b64 v[4:5], 8, v[4:5]
	v_lshl_add_u64 v[4:5], v[34:35], 0, v[4:5]
	global_load_dwordx4 v[4:7], v[4:5], off nt
.LBB0_681:
	s_or_b64 exec, exec, s[26:27]
	v_mov_b32_e32 v8, 0
	v_mov_b32_e32 v12, 0
	v_mov_b32_e32 v13, 0
	v_mov_b32_e32 v14, 0
	v_mov_b32_e32 v15, 0
	s_and_saveexec_b64 s[26:27], vcc
	s_cbranch_execz .LBB0_683
	v_or_b32_e32 v10, 2, v32
	v_ashrrev_i32_e32 v11, 31, v10
	v_lshlrev_b64 v[10:11], 8, v[10:11]
	v_lshl_add_u64 v[10:11], v[34:35], 0, v[10:11]
	global_load_dwordx4 v[12:15], v[10:11], off nt
.LBB0_683:
	s_or_b64 exec, exec, s[26:27]
	v_mov_b32_e32 v9, 0
	v_mov_b32_e32 v10, 0
	v_mov_b32_e32 v11, 0
	s_and_saveexec_b64 s[26:27], vcc
	s_cbranch_execz .LBB0_685
	v_or_b32_e32 v8, 3, v32
	v_ashrrev_i32_e32 v9, 31, v8
	v_lshlrev_b64 v[8:9], 8, v[8:9]
	v_lshl_add_u64 v[8:9], v[34:35], 0, v[8:9]
	global_load_dwordx4 v[8:11], v[8:9], off nt
.LBB0_685:
	s_or_b64 exec, exec, s[26:27]
	v_mov_b32_e32 v16, 0
	v_mov_b32_e32 v20, 0
	v_mov_b32_e32 v21, 0
	v_mov_b32_e32 v22, 0
	v_mov_b32_e32 v23, 0
	s_and_saveexec_b64 s[26:27], vcc
	s_cbranch_execz .LBB0_687
	v_or_b32_e32 v18, 4, v32
	v_ashrrev_i32_e32 v19, 31, v18
	v_lshlrev_b64 v[18:19], 8, v[18:19]
	v_lshl_add_u64 v[18:19], v[34:35], 0, v[18:19]
	global_load_dwordx4 v[20:23], v[18:19], off nt
.LBB0_687:
	s_or_b64 exec, exec, s[26:27]
	v_mov_b32_e32 v17, 0
	v_mov_b32_e32 v18, 0
	v_mov_b32_e32 v19, 0
	s_and_saveexec_b64 s[26:27], vcc
	s_cbranch_execz .LBB0_689
	v_or_b32_e32 v16, 5, v32
	v_ashrrev_i32_e32 v17, 31, v16
	v_lshlrev_b64 v[16:17], 8, v[16:17]
	v_lshl_add_u64 v[16:17], v[34:35], 0, v[16:17]
	global_load_dwordx4 v[16:19], v[16:17], off nt
.LBB0_689:
	s_or_b64 exec, exec, s[26:27]
	v_mov_b32_e32 v24, 0
	v_mov_b32_e32 v28, 0
	v_mov_b32_e32 v29, 0
	v_mov_b32_e32 v30, 0
	v_mov_b32_e32 v31, 0
	s_and_saveexec_b64 s[26:27], vcc
	s_cbranch_execz .LBB0_691
	v_or_b32_e32 v26, 6, v32
	v_ashrrev_i32_e32 v27, 31, v26
	v_lshlrev_b64 v[26:27], 8, v[26:27]
	v_lshl_add_u64 v[26:27], v[34:35], 0, v[26:27]
	global_load_dwordx4 v[28:31], v[26:27], off nt
.LBB0_691:
	s_or_b64 exec, exec, s[26:27]
	v_mov_b32_e32 v25, 0
	v_mov_b32_e32 v26, 0
	v_mov_b32_e32 v27, 0
	s_and_saveexec_b64 s[26:27], vcc
	s_cbranch_execz .LBB0_676
	v_or_b32_e32 v24, 7, v32
	v_ashrrev_i32_e32 v25, 31, v24
	v_lshlrev_b64 v[24:25], 8, v[24:25]
	v_lshl_add_u64 v[24:25], v[34:35], 0, v[24:25]
	global_load_dwordx4 v[24:27], v[24:25], off nt
	s_branch .LBB0_676

.LBB0_695:
	v_ashrrev_i32_e32 v0, 31, v36
	v_lshrrev_b32_e32 v0, 28, v0
	v_add_u32_e32 v0, v36, v0
	v_ashrrev_i32_e32 v1, 4, v0
	v_and_b32_e32 v0, -16, v0
	v_lshlrev_b32_e32 v2, 6, v1
	v_sub_u32_e32 v0, v36, v0
	v_sub_u32_e32 v192, v43, v2
	v_lshlrev_b32_e32 v32, 3, v1
	v_cmp_lt_i32_e32 vcc, -1, v0
	v_lshl_add_u64 v[34:35], v[192:193], 2, s[52:53]
	v_mov_b32_e32 v4, 0
	v_ashrrev_i32_e32 v33, 31, v32
	v_mov_b32_e32 v0, 0
	v_mov_b32_e32 v1, 0
	v_mov_b32_e32 v2, 0
	v_mov_b32_e32 v3, 0
	s_and_saveexec_b64 s[26:27], vcc
	s_cbranch_execz .LBB0_697
	v_lshlrev_b64 v[0:1], 8, v[32:33]
	v_lshl_add_u64 v[0:1], v[34:35], 0, v[0:1]
	global_load_dwordx4 v[0:3], v[0:1], off nt
